# v053 plus cross-half row max via v_permlane32_swap instead of ds_bpermute (8 sites) and FoX unmasked tile: K/V fragment LDS reads hoisted ahead of the bias init
# speedup vs baseline: 1.0140x; 1.0051x over previous
; DI void qk_acc(lptr Kt, const bf16x8 (&qf)[4], f32x16& s0, f32x16& s1, int lane) {
;     const int i = lane & 31, hi = lane >> 5;
;     const int krow = (i & 19) | ((i & 4) << 1) | ((i & 8) >> 1);
;     lptr kp = Kt + krow * KPB + hi * 16;
;     bf16x8 a0[4], a1[4];
; #pragma unroll
;     for (int d0 = 0; d0 < 4; ++d0) { a0[d0] = *(LAS bf16x8*)(kp + d0 * 32); a1[d0] = *(LAS bf16x8*)(kp + 32 * KPB + d0 * 32); }
;     __builtin_amdgcn_s_setprio(1);
; template <int MODE>
; DI void bias_init(f32x16& s0, f32x16& s1, const TP& tp, float fbm, int hi) {
; #pragma unroll
;     for (int r = 0; r < 16; ++r) {
;         const int kvc = 16 * (r >> 3) + (r & 7);
;         if (MODE == 0) { s0[r] = __builtin_fmaf(-L2E, tp.cs[kvc + 8 * hi], fbm); s1[r] = __builtin_fmaf(-L2E, tp.cs[kvc + 32 + 8 * hi], fbm); }
;         else { s0[r] = __builtin_fmaf(tp.sl, (float)kvc, fbm); s1[r] = __builtin_fmaf(tp.sl, (float)(kvc + 32), fbm); }
;     }
; }
; DI float max3_asm(float a, float b, float c) { float r; asm("v_max3_f32 %0, %1, %2, %3" : "=v"(r) : "v"(a), "v"(b), "v"(c)); return r; }
; template <bool MASK>
; DI float mask_rowmax(f32x16& s0, f32x16& s1, const TP& tp) {
;     if (MASK) {
; #pragma unroll
;         for (int r = 0; r < 16; ++r) {
;             const int kvc = 16 * (r >> 3) + (r & 7);
;             const bool v0 = tp.sel && (kvc <= tp.lim) && (kvc > tp.lim2), v1 = tp.sel && (kvc + 32 <= tp.lim) && (kvc + 32 > tp.lim2);
;             s0[r] = v0 ? s0[r] : -1e30f; s1[r] = v1 ? s1[r] : -1e30f;
;         }
;     }
;     const float seed = __builtin_fminf(s0[15], s1[15]);
;     float ma = seed, mb = seed;
; #pragma unroll
;     for (int r = 0; r < 16; r += 2) { ma = max3_asm(ma, s0[r], s1[r]); mb = max3_asm(mb, s0[r + 1], s1[r + 1]); }
;     const float mx = fmaxf(ma, mb);
;     return fmaxf(mx, __shfl_xor(mx, 32));
; }
; template <int MODE, bool MASK, bool WITH_O>
; DI void attn_tile_t(lptr Kt, lptr Vt, const bf16x8 (&qf)[4], f32x16& o0, f32x16& o1, RowState& rs, const TP& tp, int lane) {
;     const int hi = lane >> 5;
;     f32x16 s0, s1;
;     bias_init<MODE>(s0, s1, tp, tp.fb - rs.mref, hi);
;     qk_acc(Kt, qf, s0, s1, lane);
;     const float mx = mask_rowmax<MASK>(s0, s1, tp);
;     const bool was = rs.seen; rs.seen = was || (mx > -1e29f);
;     const bool trig = (mx > 8.f) || (!was && mx > -1e29f && mx < -8.f);
;     if (__builtin_expect(__any(trig), 0)) {
.LBB0_493:
	s_lshl_b32 s2, s55, 8
	s_add_i32 s26, s2, 0
	s_mul_i32 s2, s55, 0x2300
	s_add_i32 s56, s26, s2
	s_mov_b64 s[2:3], -1
	s_cmp_le_i32 s31, s42
	v_sub_f32_e32 v156, v157, v160
	v_add3_u32 v161, s56, v131, v133
	v_lshl_add_u32 v162, v126, 2, s26
	s_cbranch_scc0 .LBB0_498
	ds_read_b128 v[34:37], v162 offset:36992
	ds_read_b128 v[38:41], v162 offset:36864
	ds_read_b128 v[42:45], v162 offset:36880
	ds_read_b128 v[46:49], v162 offset:37008
	ds_read_b128 v[50:53], v162 offset:36928
	ds_read_b128 v[54:57], v162 offset:37056
	ds_read_b128 v[58:61], v162 offset:36944
	ds_read_b128 v[62:65], v162 offset:37072
	ds_read_b128 v[166:169], v161 offset:4608
	ds_read_b128 v[216:219], v161
	ds_read_b128 v[228:231], v161 offset:32
	ds_read_b128 v[232:235], v161 offset:4640
	ds_read_b128 v[236:239], v161 offset:64
	ds_read_b128 v[240:243], v161 offset:4672
	ds_read_b128 v[244:247], v161 offset:96
	ds_read_b128 v[252:255], v161 offset:4704
	s_waitcnt lgkmcnt(13)
	v_pk_fma_f32 v[88:89], v[44:45], s[80:81], v[156:157] op_sel_hi:[1,0,0]
	s_waitcnt lgkmcnt(11)
	v_pk_fma_f32 v[92:93], v[52:53], s[80:81], v[156:157] op_sel_hi:[1,0,0]
	v_pk_fma_f32 v[84:85], v[40:41], s[80:81], v[156:157] op_sel_hi:[1,0,0]
	s_waitcnt lgkmcnt(9)
	v_pk_fma_f32 v[96:97], v[60:61], s[80:81], v[156:157] op_sel_hi:[1,0,0]
	v_pk_fma_f32 v[94:95], v[58:59], s[80:81], v[156:157] op_sel_hi:[1,0,0]
	v_pk_fma_f32 v[90:91], v[50:51], s[80:81], v[156:157] op_sel_hi:[1,0,0]
	v_pk_fma_f32 v[86:87], v[42:43], s[80:81], v[156:157] op_sel_hi:[1,0,0]
	v_pk_fma_f32 v[82:83], v[38:39], s[80:81], v[156:157] op_sel_hi:[1,0,0]
	s_waitcnt lgkmcnt(8)
	v_pk_fma_f32 v[80:81], v[64:65], s[80:81], v[156:157] op_sel_hi:[1,0,0]
	v_pk_fma_f32 v[76:77], v[56:57], s[80:81], v[156:157] op_sel_hi:[1,0,0]
	v_pk_fma_f32 v[72:73], v[48:49], s[80:81], v[156:157] op_sel_hi:[1,0,0]
	v_pk_fma_f32 v[68:69], v[36:37], s[80:81], v[156:157] op_sel_hi:[1,0,0]
	v_pk_fma_f32 v[78:79], v[62:63], s[80:81], v[156:157] op_sel_hi:[1,0,0]
	v_pk_fma_f32 v[74:75], v[54:55], s[80:81], v[156:157] op_sel_hi:[1,0,0]
	v_pk_fma_f32 v[70:71], v[46:47], s[80:81], v[156:157] op_sel_hi:[1,0,0]
	v_pk_fma_f32 v[66:67], v[34:35], s[80:81], v[156:157] op_sel_hi:[1,0,0]
	s_setprio 1
	s_waitcnt lgkmcnt(6)
	v_mfma_f32_32x32x16_bf16 v[82:97], v[216:219], v[98:101], v[82:97]
	v_mfma_f32_32x32x16_bf16 v[66:81], v[166:169], v[98:101], v[66:81]
	s_waitcnt lgkmcnt(5)
	v_mfma_f32_32x32x16_bf16 v[82:97], v[228:231], v[102:105], v[82:97]
	s_waitcnt lgkmcnt(4)
	v_mfma_f32_32x32x16_bf16 v[66:81], v[232:235], v[102:105], v[66:81]
	s_waitcnt lgkmcnt(3)
	v_mfma_f32_32x32x16_bf16 v[82:97], v[236:239], v[106:109], v[82:97]
	s_waitcnt lgkmcnt(2)
	v_mfma_f32_32x32x16_bf16 v[66:81], v[240:243], v[106:109], v[66:81]
	s_waitcnt lgkmcnt(1)
	v_mfma_f32_32x32x16_bf16 v[82:97], v[244:247], v[110:113], v[82:97]
	s_waitcnt lgkmcnt(0)
	v_mfma_f32_32x32x16_bf16 v[66:81], v[252:255], v[110:113], v[66:81]
	s_setprio 0
	v_add3_u32 v228, s56, v135, v141
	ds_read_b128 v[216:219], v228 offset:18432
	ds_read_b128 v[38:41], v228 offset:23040
	ds_read_b128 v[42:45], v228 offset:18464
	ds_read_b128 v[46:49], v228 offset:23072
	ds_read_b128 v[50:53], v228 offset:18496
	ds_read_b128 v[54:57], v228 offset:23104
	ds_read_b128 v[58:61], v228 offset:18528
	ds_read_b128 v[62:65], v228 offset:23136
	s_nop 1
	v_max_f32_e32 v34, v81, v81
	v_max_f32_e32 v35, v97, v97
	v_min_f32_e32 v34, v35, v34
	v_max3_f32 v35, v34, v82, v66
	v_max3_f32 v34, v34, v83, v67
	v_and_b32_e32 v36, 64, v209
	v_max3_f32 v35, v35, v84, v68
	v_max3_f32 v34, v34, v85, v69
	v_add_u32_e32 v36, 64, v36
	v_max3_f32 v35, v35, v86, v70
	v_max3_f32 v34, v34, v87, v71
	s_mov_b32 s2, 0xefa18f08
	v_max3_f32 v35, v35, v88, v72
	v_max3_f32 v34, v34, v89, v73
	s_mov_b64 s[28:29], -1
	v_max3_f32 v35, v35, v90, v74
	v_max3_f32 v34, v34, v91, v75
	s_nop 0
	v_max3_f32 v35, v35, v92, v76
	v_max3_f32 v34, v34, v93, v77
	s_nop 0
	v_max3_f32 v35, v35, v94, v78
	v_max3_f32 v34, v34, v95, v79
	s_nop 0
	v_max3_f32 v35, v35, v96, v80
	v_max3_f32 v34, v34, v97, v81
	s_nop 0
	v_max_f32_e32 v34, v34, v34
	v_max_f32_e32 v35, v35, v35
	v_max_f32_e32 v34, v35, v34
	v_mov_b32_e32 v35, v34
	s_nop 1
	v_permlane32_swap_b32_e32 v35, v34
	s_waitcnt lgkmcnt(0)
	v_max_f32_e32 v165, v34, v35
	v_cmp_lt_f32_e64 s[26:27], s2, v165
	s_mov_b32 s2, 0x41000000
	v_cmp_lt_f32_e32 vcc, s2, v165
	s_mov_b32 s28, 0xc1000000
	v_cmp_gt_f32_e64 s[28:29], s28, v165
	s_and_b64 s[28:29], s[28:29], s[26:27]
	s_andn2_b64 s[28:29], s[28:29], s[22:23]
	s_or_b64 s[28:29], s[28:29], vcc
	s_and_b64 vcc, exec, s[28:29]
	v_mov_b32_e32 v163, v160
	v_mov_b32_e32 v164, v159
	s_cbranch_vccnz .LBB0_514

; template <int MODE>
; DI void bias_init(f32x16& s0, f32x16& s1, const TP& tp, float fbm, int hi) {
; #pragma unroll
;     for (int r = 0; r < 16; ++r) {
;         const int kvc = 16 * (r >> 3) + (r & 7);
;         if (MODE == 0) { s0[r] = __builtin_fmaf(-L2E, tp.cs[kvc + 8 * hi], fbm); s1[r] = __builtin_fmaf(-L2E, tp.cs[kvc + 32 + 8 * hi], fbm); }
;         else { s0[r] = __builtin_fmaf(tp.sl, (float)kvc, fbm); s1[r] = __builtin_fmaf(tp.sl, (float)(kvc + 32), fbm); }
;     }
; }
; DI float max3_asm(float a, float b, float c) { float r; asm("v_max3_f32 %0, %1, %2, %3" : "=v"(r) : "v"(a), "v"(b), "v"(c)); return r; }
; template <bool MASK>
; DI float mask_rowmax(f32x16& s0, f32x16& s1, const TP& tp) {
;     if (MASK) {
; #pragma unroll
;         for (int r = 0; r < 16; ++r) {
;             const int kvc = 16 * (r >> 3) + (r & 7);
;             const bool v0 = tp.sel && (kvc <= tp.lim) && (kvc > tp.lim2), v1 = tp.sel && (kvc + 32 <= tp.lim) && (kvc + 32 > tp.lim2);
;             s0[r] = v0 ? s0[r] : -1e30f; s1[r] = v1 ? s1[r] : -1e30f;
;         }
;     }
;     const float seed = __builtin_fminf(s0[15], s1[15]);
;     float ma = seed, mb = seed;
; #pragma unroll
;     for (int r = 0; r < 16; r += 2) { ma = max3_asm(ma, s0[r], s1[r]); mb = max3_asm(mb, s0[r + 1], s1[r + 1]); }
;     const float mx = fmaxf(ma, mb);
;     return fmaxf(mx, __shfl_xor(mx, 32));
; }
; template <int MODE, bool MASK, bool WITH_O>
; DI void attn_tile_t(lptr Kt, lptr Vt, const bf16x8 (&qf)[4], f32x16& o0, f32x16& o1, RowState& rs, const TP& tp, int lane) {
;     const int hi = lane >> 5;
;     f32x16 s0, s1;
;     bias_init<MODE>(s0, s1, tp, tp.fb - rs.mref, hi);
;     qk_acc(Kt, qf, s0, s1, lane);
;     const float mx = mask_rowmax<MASK>(s0, s1, tp);
;     const bool was = rs.seen; rs.seen = was || (mx > -1e29f);
;     const bool trig = (mx > 8.f) || (!was && mx > -1e29f && mx < -8.f);
;     if (__builtin_expect(__any(trig), 0)) {
.LBB0_498:
	s_and_b64 vcc, exec, s[2:3]
	s_cbranch_vccz .LBB0_503
	s_nop 8
	ds_read_b128 v[50:53], v162 offset:36992
	ds_read_b128 v[34:37], v162 offset:36864
	ds_read_b128 v[38:41], v162 offset:36880
	ds_read_b128 v[54:57], v162 offset:37008
	ds_read_b128 v[42:45], v162 offset:36928
	ds_read_b128 v[58:61], v162 offset:37056
	ds_read_b128 v[46:49], v162 offset:36944
	ds_read_b128 v[62:65], v162 offset:37072
	ds_read_b128 v[66:69], v161 offset:4608
	ds_read_b128 v[70:73], v161
	ds_read_b128 v[74:77], v161 offset:32
	ds_read_b128 v[78:81], v161 offset:4640
	ds_read_b128 v[82:85], v161 offset:64
	ds_read_b128 v[86:89], v161 offset:4672
	ds_read_b128 v[90:93], v161 offset:96
	ds_read_b128 v[94:97], v161 offset:4704
	s_waitcnt lgkmcnt(11)
	v_pk_fma_f32 v[44:45], v[44:45], s[80:81], v[156:157] op_sel_hi:[1,0,0]
	v_pk_fma_f32 v[40:41], v[40:41], s[80:81], v[156:157] op_sel_hi:[1,0,0]
	v_pk_fma_f32 v[36:37], v[36:37], s[80:81], v[156:157] op_sel_hi:[1,0,0]
	s_waitcnt lgkmcnt(9)
	v_pk_fma_f32 v[46:47], v[46:47], s[80:81], v[156:157] op_sel_hi:[1,0,0]
	v_pk_fma_f32 v[42:43], v[42:43], s[80:81], v[156:157] op_sel_hi:[1,0,0]
	v_pk_fma_f32 v[38:39], v[38:39], s[80:81], v[156:157] op_sel_hi:[1,0,0]
	v_pk_fma_f32 v[34:35], v[34:35], s[80:81], v[156:157] op_sel_hi:[1,0,0]
	v_pk_fma_f32 v[56:57], v[56:57], s[80:81], v[156:157] op_sel_hi:[1,0,0]
	v_pk_fma_f32 v[52:53], v[52:53], s[80:81], v[156:157] op_sel_hi:[1,0,0]
	v_pk_fma_f32 v[54:55], v[54:55], s[80:81], v[156:157] op_sel_hi:[1,0,0]
	v_pk_fma_f32 v[50:51], v[50:51], s[80:81], v[156:157] op_sel_hi:[1,0,0]
	v_pk_fma_f32 v[48:49], v[48:49], s[80:81], v[156:157] op_sel_hi:[1,0,0]
	s_waitcnt lgkmcnt(8)
	v_pk_fma_f32 v[64:65], v[64:65], s[80:81], v[156:157] op_sel_hi:[1,0,0]
	v_pk_fma_f32 v[60:61], v[60:61], s[80:81], v[156:157] op_sel_hi:[1,0,0]
	v_pk_fma_f32 v[62:63], v[62:63], s[80:81], v[156:157] op_sel_hi:[1,0,0]
	v_pk_fma_f32 v[58:59], v[58:59], s[80:81], v[156:157] op_sel_hi:[1,0,0]
	s_setprio 1
	s_waitcnt lgkmcnt(6)
	v_mfma_f32_32x32x16_bf16 v[34:49], v[70:73], v[98:101], v[34:49]
	v_mfma_f32_32x32x16_bf16 v[50:65], v[66:69], v[98:101], v[50:65]
	s_waitcnt lgkmcnt(5)
	v_mfma_f32_32x32x16_bf16 v[34:49], v[74:77], v[102:105], v[34:49]
	s_waitcnt lgkmcnt(4)
	v_mfma_f32_32x32x16_bf16 v[50:65], v[78:81], v[102:105], v[50:65]
	s_waitcnt lgkmcnt(3)
	v_mfma_f32_32x32x16_bf16 v[34:49], v[82:85], v[106:109], v[34:49]
	s_waitcnt lgkmcnt(2)
	v_mfma_f32_32x32x16_bf16 v[50:65], v[86:89], v[106:109], v[50:65]
	s_waitcnt lgkmcnt(1)
	v_mfma_f32_32x32x16_bf16 v[34:49], v[90:93], v[110:113], v[34:49]
	s_waitcnt lgkmcnt(0)
	v_mfma_f32_32x32x16_bf16 v[50:65], v[94:97], v[110:113], v[50:65]
	s_setprio 0
	v_cmp_lt_i32_e32 vcc, 0, v158
	s_mov_b32 s2, 0xefa18f08
	s_nop 6
	v_cndmask_b32_e32 v72, v210, v35, vcc
	v_cmp_lt_i32_e32 vcc, -1, v158
	s_nop 1
	v_cndmask_b32_e32 v76, v210, v34, vcc
	v_cmp_lt_i32_e32 vcc, 32, v158
	s_nop 1
	v_cndmask_b32_e32 v66, v210, v51, vcc
	v_cmp_lt_i32_e32 vcc, 31, v158
	s_nop 1
	v_cndmask_b32_e32 v68, v210, v50, vcc
	v_cmp_lt_i32_e32 vcc, 2, v158
	s_nop 1
	v_cndmask_b32_e32 v71, v210, v37, vcc
	v_cmp_lt_i32_e32 vcc, 1, v158
	s_nop 1
	v_cndmask_b32_e32 v75, v210, v36, vcc
	v_cmp_lt_i32_e32 vcc, 34, v158
	s_nop 1
	v_cndmask_b32_e32 v53, v210, v53, vcc
	v_cmp_lt_i32_e32 vcc, 33, v158
	s_nop 1
	v_cndmask_b32_e32 v67, v210, v52, vcc
	v_cmp_lt_i32_e32 vcc, 4, v158
	s_nop 1
	v_cndmask_b32_e32 v70, v210, v39, vcc
	v_cmp_lt_i32_e32 vcc, 3, v158
	s_nop 1
	v_cndmask_b32_e32 v74, v210, v38, vcc
	v_cmp_lt_i32_e32 vcc, 36, v158
	s_nop 1
	v_cndmask_b32_e32 v51, v210, v55, vcc
	v_cmp_lt_i32_e32 vcc, 35, v158
	s_nop 1
	v_cndmask_b32_e32 v54, v210, v54, vcc
	v_cmp_lt_i32_e32 vcc, 6, v158
	s_nop 1
	v_cndmask_b32_e32 v69, v210, v41, vcc
	v_cmp_lt_i32_e32 vcc, 5, v158
	s_nop 1
	v_cndmask_b32_e32 v73, v210, v40, vcc
	v_cmp_lt_i32_e32 vcc, 38, v158
	s_nop 1
	v_cndmask_b32_e32 v50, v210, v57, vcc
	v_cmp_lt_i32_e32 vcc, 37, v158
	s_nop 1
	v_cndmask_b32_e32 v52, v210, v56, vcc
	v_cmp_lt_i32_e32 vcc, 16, v158
	s_nop 1
	v_cndmask_b32_e32 v55, v210, v43, vcc
	v_cmp_lt_i32_e32 vcc, 15, v158
	s_nop 1
	v_cndmask_b32_e32 v57, v210, v42, vcc
	v_cmp_lt_i32_e32 vcc, 48, v158
	s_nop 1
	v_cndmask_b32_e32 v38, v210, v59, vcc
	v_cmp_lt_i32_e32 vcc, 47, v158
	s_nop 1
	v_cndmask_b32_e32 v41, v210, v58, vcc
	v_cmp_lt_i32_e32 vcc, 18, v158
	s_nop 1
	v_cndmask_b32_e32 v45, v210, v45, vcc
	v_cmp_lt_i32_e32 vcc, 17, v158
	s_nop 1
	v_cndmask_b32_e32 v56, v210, v44, vcc
	v_cmp_lt_i32_e32 vcc, 50, v158
	s_nop 1
	v_cndmask_b32_e32 v36, v210, v61, vcc
	v_cmp_lt_i32_e32 vcc, 49, v158
	s_nop 1
	v_cndmask_b32_e32 v40, v210, v60, vcc
	v_cmp_lt_i32_e32 vcc, 20, v158
	s_nop 1
	v_cndmask_b32_e32 v43, v210, v47, vcc
	v_cmp_lt_i32_e32 vcc, 19, v158
	s_nop 1
	v_cndmask_b32_e32 v46, v210, v46, vcc
	v_cmp_lt_i32_e32 vcc, 52, v158
	s_nop 1
	v_cndmask_b32_e32 v35, v210, v63, vcc
	v_cmp_lt_i32_e32 vcc, 51, v158
	s_nop 1
	v_cndmask_b32_e32 v39, v210, v62, vcc
	v_cmp_lt_i32_e32 vcc, 22, v158
	s_nop 1
	v_cndmask_b32_e32 v42, v210, v49, vcc
	v_cmp_lt_i32_e32 vcc, 21, v158
	v_and_b32_e32 v49, 64, v209
	v_add_u32_e32 v49, 64, v49
	v_cndmask_b32_e32 v44, v210, v48, vcc
	v_cmp_lt_i32_e32 vcc, 54, v158
	v_max_f32_e32 v48, v42, v42
	s_nop 0
	v_cndmask_b32_e32 v34, v210, v65, vcc
	v_max_f32_e32 v47, v34, v34
	v_min_f32_e32 v47, v48, v47
	v_max3_f32 v48, v47, v76, v68
	v_max3_f32 v47, v47, v72, v66
	v_cmp_lt_i32_e32 vcc, 53, v158
	v_max3_f32 v48, v48, v75, v67
	v_max3_f32 v47, v47, v71, v53
	s_nop 0
	v_max3_f32 v48, v48, v74, v54
	v_max3_f32 v47, v47, v70, v51
	s_nop 0
	v_cndmask_b32_e32 v37, v210, v64, vcc
	v_max3_f32 v48, v48, v73, v52
	v_max3_f32 v47, v47, v69, v50
	s_nop 0
	v_max3_f32 v48, v48, v57, v41
	v_max3_f32 v47, v47, v55, v38
	s_nop 0
	v_max3_f32 v48, v48, v56, v40
	v_max3_f32 v47, v47, v45, v36
	s_nop 0
	v_max3_f32 v48, v48, v46, v39
	v_max3_f32 v47, v47, v43, v35
	s_nop 0
	v_max3_f32 v48, v48, v44, v37
	v_max3_f32 v47, v47, v42, v34
	s_nop 0
	v_max_f32_e32 v47, v47, v47
	v_max_f32_e32 v48, v48, v48
	v_max_f32_e32 v47, v48, v47
	v_mov_b32_e32 v48, v47
	s_nop 1
	v_permlane32_swap_b32_e32 v48, v47
	s_waitcnt lgkmcnt(0)
	v_max_f32_e32 v47, v47, v48
	v_cmp_lt_f32_e64 s[26:27], s2, v47
	s_mov_b32 s2, 0x41000000
	v_cmp_lt_f32_e32 vcc, s2, v47
	s_mov_b32 s2, 0xc1000000
	v_cmp_gt_f32_e64 s[2:3], s2, v47
	s_and_b64 s[2:3], s[2:3], s[26:27]
	s_andn2_b64 s[2:3], s[2:3], s[22:23]
	s_or_b64 s[2:3], s[2:3], vcc
	s_and_b64 vcc, exec, s[2:3]
	s_cbranch_vccnz .LBB0_515

; template <int MODE>
; DI void bias_init(f32x16& s0, f32x16& s1, const TP& tp, float fbm, int hi) {
; #pragma unroll
;     for (int r = 0; r < 16; ++r) {
;         const int kvc = 16 * (r >> 3) + (r & 7);
;         if (MODE == 0) { s0[r] = __builtin_fmaf(-L2E, tp.cs[kvc + 8 * hi], fbm); s1[r] = __builtin_fmaf(-L2E, tp.cs[kvc + 32 + 8 * hi], fbm); }
;         else { s0[r] = __builtin_fmaf(tp.sl, (float)kvc, fbm); s1[r] = __builtin_fmaf(tp.sl, (float)(kvc + 32), fbm); }
;     }
; }
; DI float max3_asm(float a, float b, float c) { float r; asm("v_max3_f32 %0, %1, %2, %3" : "=v"(r) : "v"(a), "v"(b), "v"(c)); return r; }
; template <bool MASK>
; DI float mask_rowmax(f32x16& s0, f32x16& s1, const TP& tp) {
;     if (MASK) {
; #pragma unroll
;         for (int r = 0; r < 16; ++r) {
;             const int kvc = 16 * (r >> 3) + (r & 7);
;             const bool v0 = tp.sel && (kvc <= tp.lim) && (kvc > tp.lim2), v1 = tp.sel && (kvc + 32 <= tp.lim) && (kvc + 32 > tp.lim2);
;             s0[r] = v0 ? s0[r] : -1e30f; s1[r] = v1 ? s1[r] : -1e30f;
;         }
;     }
;     const float seed = __builtin_fminf(s0[15], s1[15]);
;     float ma = seed, mb = seed;
; #pragma unroll
;     for (int r = 0; r < 16; r += 2) { ma = max3_asm(ma, s0[r], s1[r]); mb = max3_asm(mb, s0[r + 1], s1[r + 1]); }
;     const float mx = fmaxf(ma, mb);
;     return fmaxf(mx, __shfl_xor(mx, 32));
; }
; template <int MODE, bool MASK, bool WITH_O>
; DI void attn_tile_t(lptr Kt, lptr Vt, const bf16x8 (&qf)[4], f32x16& o0, f32x16& o1, RowState& rs, const TP& tp, int lane) {
;     const int hi = lane >> 5;
;     f32x16 s0, s1;
;     bias_init<MODE>(s0, s1, tp, tp.fb - rs.mref, hi);
;     qk_acc(Kt, qf, s0, s1, lane);
;     const float mx = mask_rowmax<MASK>(s0, s1, tp);
;     const bool was = rs.seen; rs.seen = was || (mx > -1e29f);
;     const bool trig = (mx > 8.f) || (!was && mx > -1e29f && mx < -8.f);
;     if (__builtin_expect(__any(trig), 0)) {
.LBB0_526:
	v_cvt_f32_i32_e32 v2, v47
	s_and_b32 s43, s30, 1
	s_mul_i32 s2, s43, 0x2400
	s_add_i32 s52, s2, 0
	v_mul_f32_e32 v50, v150, v2
	s_cmp_gt_i32 s42, s29
	s_mov_b64 s[2:3], -1
	s_cbranch_scc1 .LBB0_535
	s_mov_b32 s2, 2.0
	v_sub_f32_e32 v2, v50, v49
	s_mov_b32 s3, 0x40400000
	v_add3_u32 v51, s52, v131, v133
	v_pk_fma_f32 v[20:21], v[80:81], s[2:3], v[2:3] op_sel_hi:[1,1,0]
	s_mov_b32 s2, 4.0
	ds_read_b128 v[52:55], v51 offset:4608
	ds_read_b128 v[56:59], v51
	ds_read_b128 v[60:63], v51 offset:32
	ds_read_b128 v[64:67], v51 offset:4640
	ds_read_b128 v[68:71], v51 offset:64
	ds_read_b128 v[88:91], v51 offset:4672
	ds_read_b128 v[92:95], v51 offset:96
	ds_read_b128 v[114:117], v51 offset:4704
	s_mov_b32 s3, 0x40a00000
	v_pk_fma_f32 v[22:23], v[80:81], s[2:3], v[2:3] op_sel_hi:[1,1,0]
	s_mov_b32 s2, 0x40c00000
	s_mov_b32 s3, 0x40e00000
	v_pk_fma_f32 v[24:25], v[80:81], s[2:3], v[2:3] op_sel_hi:[1,1,0]
	s_mov_b32 s2, 0x41800000
	s_mov_b32 s3, 0x41880000
	v_pk_fma_f32 v[26:27], v[80:81], s[2:3], v[2:3] op_sel_hi:[1,1,0]
	s_mov_b32 s2, 0x41900000
	s_mov_b32 s3, 0x41980000
	v_pk_fma_f32 v[28:29], v[80:81], s[2:3], v[2:3] op_sel_hi:[1,1,0]
	s_mov_b32 s2, 0x41a00000
	s_mov_b32 s3, 0x41a80000
	v_mov_b32_e32 v79, v78
	v_fma_f32 v18, 0, v78, v2
	v_add_f32_e32 v19, v78, v2
	v_pk_fma_f32 v[30:31], v[80:81], s[2:3], v[2:3] op_sel_hi:[1,1,0]
	v_pk_fma_f32 v[32:33], v[80:81], s[18:19], v[2:3] op_sel_hi:[1,1,0]
	v_pk_fma_f32 v[16:17], v[78:79], s[4:5], v[2:3] op_sel_hi:[1,1,0]
	v_pk_fma_f32 v[14:15], v[78:79], s[14:15], v[2:3] op_sel_hi:[1,1,0]
	v_pk_fma_f32 v[12:13], v[78:79], s[16:17], v[2:3] op_sel_hi:[1,1,0]
	v_pk_fma_f32 v[10:11], v[78:79], s[94:95], v[2:3] op_sel_hi:[1,1,0]
	v_pk_fma_f32 v[8:9], v[78:79], s[96:97], v[2:3] op_sel_hi:[1,1,0]
	v_pk_fma_f32 v[6:7], v[78:79], s[84:85], v[2:3] op_sel_hi:[1,1,0]
	v_pk_fma_f32 v[4:5], v[78:79], s[72:73], v[2:3] op_sel_hi:[1,1,0]
	v_pk_fma_f32 v[2:3], v[82:83], s[44:45], v[2:3] op_sel_hi:[1,1,0]
	s_setprio 1
	s_waitcnt vmcnt(4) lgkmcnt(6)
	v_mfma_f32_32x32x16_bf16 v[18:33], v[56:59], v[98:101], v[18:33]
	v_mfma_f32_32x32x16_bf16 v[2:17], v[52:55], v[98:101], v[2:17]
	s_waitcnt vmcnt(3) lgkmcnt(5)
	v_mfma_f32_32x32x16_bf16 v[18:33], v[60:63], v[102:105], v[18:33]
	s_waitcnt lgkmcnt(4)
	v_mfma_f32_32x32x16_bf16 v[2:17], v[64:67], v[102:105], v[2:17]
	s_waitcnt vmcnt(2) lgkmcnt(3)
	v_mfma_f32_32x32x16_bf16 v[18:33], v[68:71], v[106:109], v[18:33]
	s_waitcnt lgkmcnt(2)
	v_mfma_f32_32x32x16_bf16 v[2:17], v[88:91], v[106:109], v[2:17]
	s_waitcnt vmcnt(1) lgkmcnt(1)
	v_mfma_f32_32x32x16_bf16 v[18:33], v[92:95], v[110:113], v[18:33]
	s_waitcnt lgkmcnt(0)
	v_mfma_f32_32x32x16_bf16 v[2:17], v[114:117], v[110:113], v[2:17]
	s_setprio 0
	s_nop 10
	v_max_f32_e32 v51, v17, v17
	v_max_f32_e32 v52, v33, v33
	v_min_f32_e32 v51, v52, v51
	v_max3_f32 v52, v51, v18, v2
	v_max3_f32 v51, v51, v19, v3
	v_and_b32_e32 v53, 64, v209
	v_max3_f32 v52, v52, v20, v4
	v_max3_f32 v51, v51, v21, v5
	v_add_u32_e32 v53, 64, v53
	v_max3_f32 v52, v52, v22, v6
	v_max3_f32 v51, v51, v23, v7
	s_mov_b32 s2, 0xefa18f08
	v_max3_f32 v52, v52, v24, v8
	v_max3_f32 v51, v51, v25, v9
	s_mov_b64 s[26:27], -1
	v_max3_f32 v52, v52, v26, v10
	v_max3_f32 v51, v51, v27, v11
	s_nop 0
	v_max3_f32 v52, v52, v28, v12
	v_max3_f32 v51, v51, v29, v13
	s_nop 0
	v_max3_f32 v52, v52, v30, v14
	v_max3_f32 v51, v51, v31, v15
	s_nop 0
	v_max3_f32 v52, v52, v32, v16
	v_max3_f32 v51, v51, v33, v17
	s_nop 0
	v_max_f32_e32 v51, v51, v51
	v_max_f32_e32 v52, v52, v52
	v_max_f32_e32 v51, v52, v51
	v_mov_b32_e32 v52, v51
	s_nop 1
	v_permlane32_swap_b32_e32 v52, v51
	s_waitcnt lgkmcnt(0)
	v_max_f32_e32 v53, v51, v52
	v_cmp_lt_f32_e64 s[24:25], s2, v53
	s_mov_b32 s2, 0x41000000
	v_cmp_lt_f32_e32 vcc, s2, v53
	s_mov_b32 s26, 0xc1000000
	v_cmp_gt_f32_e64 s[26:27], s26, v53
	s_and_b64 s[26:27], s[26:27], s[24:25]
	s_andn2_b64 s[26:27], s[26:27], s[0:1]
	s_or_b64 s[26:27], s[26:27], vcc
	s_and_b64 vcc, exec, s[26:27]
	v_mov_b32_e32 v51, v49
	v_mov_b32_e32 v52, v46
	s_cbranch_vccnz .LBB0_540

; template <int MODE>
; DI void bias_init(f32x16& s0, f32x16& s1, const TP& tp, float fbm, int hi) {
; #pragma unroll
;     for (int r = 0; r < 16; ++r) {
;         const int kvc = 16 * (r >> 3) + (r & 7);
;         if (MODE == 0) { s0[r] = __builtin_fmaf(-L2E, tp.cs[kvc + 8 * hi], fbm); s1[r] = __builtin_fmaf(-L2E, tp.cs[kvc + 32 + 8 * hi], fbm); }
;         else { s0[r] = __builtin_fmaf(tp.sl, (float)kvc, fbm); s1[r] = __builtin_fmaf(tp.sl, (float)(kvc + 32), fbm); }
;     }
; }
; DI float max3_asm(float a, float b, float c) { float r; asm("v_max3_f32 %0, %1, %2, %3" : "=v"(r) : "v"(a), "v"(b), "v"(c)); return r; }
; template <bool MASK>
; DI float mask_rowmax(f32x16& s0, f32x16& s1, const TP& tp) {
;     if (MASK) {
; #pragma unroll
;         for (int r = 0; r < 16; ++r) {
;             const int kvc = 16 * (r >> 3) + (r & 7);
;             const bool v0 = tp.sel && (kvc <= tp.lim) && (kvc > tp.lim2), v1 = tp.sel && (kvc + 32 <= tp.lim) && (kvc + 32 > tp.lim2);
;             s0[r] = v0 ? s0[r] : -1e30f; s1[r] = v1 ? s1[r] : -1e30f;
;         }
;     }
;     const float seed = __builtin_fminf(s0[15], s1[15]);
;     float ma = seed, mb = seed;
; #pragma unroll
;     for (int r = 0; r < 16; r += 2) { ma = max3_asm(ma, s0[r], s1[r]); mb = max3_asm(mb, s0[r + 1], s1[r + 1]); }
;     const float mx = fmaxf(ma, mb);
;     return fmaxf(mx, __shfl_xor(mx, 32));
; }
; template <int MODE, bool MASK, bool WITH_O>
; DI void attn_tile_t(lptr Kt, lptr Vt, const bf16x8 (&qf)[4], f32x16& o0, f32x16& o1, RowState& rs, const TP& tp, int lane) {
;     const int hi = lane >> 5;
;     f32x16 s0, s1;
;     bias_init<MODE>(s0, s1, tp, tp.fb - rs.mref, hi);
;     qk_acc(Kt, qf, s0, s1, lane);
;     const float mx = mask_rowmax<MASK>(s0, s1, tp);
;     const bool was = rs.seen; rs.seen = was || (mx > -1e29f);
;     const bool trig = (mx > 8.f) || (!was && mx > -1e29f && mx < -8.f);
;     if (__builtin_expect(__any(trig), 0)) {
.LBB0_535:
	s_and_b64 vcc, exec, s[2:3]
	s_cbranch_vccz .LBB0_531
	v_sub_f32_e32 v18, v50, v49
	s_mov_b32 s2, 2.0
	v_mov_b32_e32 v79, v78
	s_mov_b32 s3, 0x40400000
	v_pk_fma_f32 v[32:33], v[78:79], s[4:5], v[18:19] op_sel_hi:[1,1,0]
	v_pk_fma_f32 v[30:31], v[78:79], s[14:15], v[18:19] op_sel_hi:[1,1,0]
	v_pk_fma_f32 v[28:29], v[78:79], s[16:17], v[18:19] op_sel_hi:[1,1,0]
	v_pk_fma_f32 v[26:27], v[78:79], s[94:95], v[18:19] op_sel_hi:[1,1,0]
	v_pk_fma_f32 v[24:25], v[78:79], s[96:97], v[18:19] op_sel_hi:[1,1,0]
	v_pk_fma_f32 v[22:23], v[78:79], s[84:85], v[18:19] op_sel_hi:[1,1,0]
	v_pk_fma_f32 v[20:21], v[78:79], s[72:73], v[18:19] op_sel_hi:[1,1,0]
	v_add3_u32 v79, s52, v131, v133
	v_pk_fma_f32 v[4:5], v[80:81], s[2:3], v[18:19] op_sel_hi:[1,1,0]
	s_mov_b32 s2, 4.0
	ds_read_b128 v[50:53], v79 offset:4608
	ds_read_b128 v[54:57], v79
	ds_read_b128 v[58:61], v79 offset:32
	ds_read_b128 v[62:65], v79 offset:4640
	ds_read_b128 v[66:69], v79 offset:64
	ds_read_b128 v[70:73], v79 offset:4672
	ds_read_b128 v[88:91], v79 offset:96
	ds_read_b128 v[92:95], v79 offset:4704
	s_mov_b32 s3, 0x40a00000
	v_pk_fma_f32 v[6:7], v[80:81], s[2:3], v[18:19] op_sel_hi:[1,1,0]
	s_mov_b32 s2, 0x40c00000
	s_mov_b32 s3, 0x40e00000
	v_pk_fma_f32 v[8:9], v[80:81], s[2:3], v[18:19] op_sel_hi:[1,1,0]
	s_mov_b32 s2, 0x41800000
	s_mov_b32 s3, 0x41880000
	v_pk_fma_f32 v[10:11], v[80:81], s[2:3], v[18:19] op_sel_hi:[1,1,0]
	s_mov_b32 s2, 0x41900000
	s_mov_b32 s3, 0x41980000
	v_pk_fma_f32 v[12:13], v[80:81], s[2:3], v[18:19] op_sel_hi:[1,1,0]
	s_mov_b32 s2, 0x41a00000
	s_mov_b32 s3, 0x41a80000
	v_fma_f32 v2, 0, v78, v18
	v_add_f32_e32 v3, v78, v18
	v_pk_fma_f32 v[14:15], v[80:81], s[2:3], v[18:19] op_sel_hi:[1,1,0]
	v_pk_fma_f32 v[16:17], v[80:81], s[18:19], v[18:19] op_sel_hi:[1,1,0]
	v_pk_fma_f32 v[18:19], v[82:83], s[44:45], v[18:19] op_sel_hi:[1,1,0]
	s_setprio 1
	s_waitcnt vmcnt(4) lgkmcnt(6)
	v_mfma_f32_32x32x16_bf16 v[2:17], v[54:57], v[98:101], v[2:17]
	v_mfma_f32_32x32x16_bf16 v[18:33], v[50:53], v[98:101], v[18:33]
	s_waitcnt vmcnt(3) lgkmcnt(5)
	v_mfma_f32_32x32x16_bf16 v[2:17], v[58:61], v[102:105], v[2:17]
	s_waitcnt lgkmcnt(4)
	v_mfma_f32_32x32x16_bf16 v[18:33], v[62:65], v[102:105], v[18:33]
	s_waitcnt vmcnt(2) lgkmcnt(3)
	v_mfma_f32_32x32x16_bf16 v[2:17], v[66:69], v[106:109], v[2:17]
	s_waitcnt lgkmcnt(2)
	v_mfma_f32_32x32x16_bf16 v[18:33], v[70:73], v[106:109], v[18:33]
	s_waitcnt vmcnt(1) lgkmcnt(1)
	v_mfma_f32_32x32x16_bf16 v[2:17], v[88:91], v[110:113], v[2:17]
	s_waitcnt lgkmcnt(0)
	v_mfma_f32_32x32x16_bf16 v[18:33], v[92:95], v[110:113], v[18:33]
	s_setprio 0
	v_cmp_lt_i32_e32 vcc, 0, v48
	s_mov_b32 s2, 0xefa18f08
	s_nop 6
	v_cndmask_b32_e32 v51, v210, v3, vcc
	v_cmp_lt_i32_e32 vcc, -1, v48
	s_nop 1
	v_cndmask_b32_e32 v55, v210, v2, vcc
	v_cmp_lt_i32_e32 vcc, 32, v48
	s_nop 1
	v_cndmask_b32_e32 v53, v210, v19, vcc
	v_cmp_lt_i32_e32 vcc, 31, v48
	s_nop 1
	v_cndmask_b32_e32 v58, v210, v18, vcc
	v_cmp_lt_i32_e32 vcc, 2, v48
	s_nop 1
	v_cndmask_b32_e32 v50, v210, v5, vcc
	v_cmp_lt_i32_e32 vcc, 1, v48
	s_nop 1
	v_cndmask_b32_e32 v57, v210, v4, vcc
	v_cmp_lt_i32_e32 vcc, 34, v48
	s_nop 1
	v_cndmask_b32_e32 v21, v210, v21, vcc
	v_cmp_lt_i32_e32 vcc, 33, v48
	s_nop 1
	v_cndmask_b32_e32 v59, v210, v20, vcc
	v_cmp_lt_i32_e32 vcc, 4, v48
	s_nop 1
	v_cndmask_b32_e32 v18, v210, v7, vcc
	v_cmp_lt_i32_e32 vcc, 3, v48
	s_nop 1
	v_cndmask_b32_e32 v54, v210, v6, vcc
	v_cmp_lt_i32_e32 vcc, 36, v48
	s_nop 1
	v_cndmask_b32_e32 v20, v210, v23, vcc
	v_cmp_lt_i32_e32 vcc, 35, v48
	s_nop 1
	v_cndmask_b32_e32 v56, v210, v22, vcc
	v_cmp_lt_i32_e32 vcc, 6, v48
	s_nop 1
	v_cndmask_b32_e32 v9, v210, v9, vcc
	v_cmp_lt_i32_e32 vcc, 5, v48
	s_nop 1
	v_cndmask_b32_e32 v52, v210, v8, vcc
	v_cmp_lt_i32_e32 vcc, 38, v48
	s_nop 1
	v_cndmask_b32_e32 v19, v210, v25, vcc
	v_cmp_lt_i32_e32 vcc, 37, v48
	s_nop 1
	v_cndmask_b32_e32 v25, v210, v24, vcc
	v_cmp_lt_i32_e32 vcc, 16, v48
	s_nop 1
	v_cndmask_b32_e32 v6, v210, v11, vcc
	v_cmp_lt_i32_e32 vcc, 15, v48
	s_nop 1
	v_cndmask_b32_e32 v22, v210, v10, vcc
	v_cmp_lt_i32_e32 vcc, 48, v48
	s_nop 1
	v_cndmask_b32_e32 v8, v210, v27, vcc
	v_cmp_lt_i32_e32 vcc, 47, v48
	s_nop 1
	v_cndmask_b32_e32 v24, v210, v26, vcc
	v_cmp_lt_i32_e32 vcc, 18, v48
	v_and_b32_e32 v26, 64, v209
	v_add_u32_e32 v26, 64, v26
	v_cndmask_b32_e32 v4, v210, v13, vcc
	v_cmp_lt_i32_e32 vcc, 17, v48
	s_nop 1
	v_cndmask_b32_e32 v13, v210, v12, vcc
	v_cmp_lt_i32_e32 vcc, 50, v48
	s_nop 1
	v_cndmask_b32_e32 v7, v210, v29, vcc
	v_cmp_lt_i32_e32 vcc, 49, v48
	s_nop 1
	v_cndmask_b32_e32 v23, v210, v28, vcc
	v_cmp_lt_i32_e32 vcc, 20, v48
	s_nop 1
	v_cndmask_b32_e32 v3, v210, v15, vcc
	v_cmp_lt_i32_e32 vcc, 19, v48
	s_nop 1
	v_cndmask_b32_e32 v11, v210, v14, vcc
	v_cmp_lt_i32_e32 vcc, 52, v48
	s_nop 1
	v_cndmask_b32_e32 v5, v210, v31, vcc
	v_cmp_lt_i32_e32 vcc, 51, v48
	s_nop 1
	v_cndmask_b32_e32 v14, v210, v30, vcc
	v_cmp_lt_i32_e32 vcc, 22, v48
	s_nop 1
	v_cndmask_b32_e32 v2, v210, v17, vcc
	v_cmp_lt_i32_e32 vcc, 21, v48
	s_nop 1
	v_cndmask_b32_e32 v10, v210, v16, vcc
	v_cmp_lt_i32_e32 vcc, 54, v48
	v_max_f32_e32 v16, v2, v2
	s_nop 0
	v_cndmask_b32_e32 v17, v210, v33, vcc
	v_max_f32_e32 v15, v17, v17
	v_min_f32_e32 v15, v16, v15
	v_max3_f32 v16, v15, v55, v58
	v_max3_f32 v15, v15, v51, v53
	v_cmp_lt_i32_e32 vcc, 53, v48
	v_max3_f32 v16, v16, v57, v59
	v_max3_f32 v15, v15, v50, v21
	s_nop 0
	v_max3_f32 v16, v16, v54, v56
	v_max3_f32 v15, v15, v18, v20
	s_nop 0
	v_cndmask_b32_e32 v12, v210, v32, vcc
	v_max3_f32 v16, v16, v52, v25
	v_max3_f32 v15, v15, v9, v19
	s_nop 0
	v_max3_f32 v16, v16, v22, v24
	v_max3_f32 v15, v15, v6, v8
	s_nop 0
	v_max3_f32 v16, v16, v13, v23
	v_max3_f32 v15, v15, v4, v7
	s_nop 0
	v_max3_f32 v16, v16, v11, v14
	v_max3_f32 v15, v15, v3, v5
	s_nop 0
	v_max3_f32 v16, v16, v10, v12
	v_max3_f32 v15, v15, v2, v17
	s_nop 0
	v_max_f32_e32 v15, v15, v15
	v_max_f32_e32 v16, v16, v16
	v_max_f32_e32 v15, v16, v15
	v_mov_b32_e32 v16, v15
	s_nop 1
	v_permlane32_swap_b32_e32 v16, v15
	s_waitcnt lgkmcnt(0)
	v_max_f32_e32 v15, v15, v16
	v_cmp_lt_f32_e64 s[24:25], s2, v15
	s_mov_b32 s2, 0x41000000
	v_cmp_lt_f32_e32 vcc, s2, v15
	s_mov_b32 s2, 0xc1000000
	v_cmp_gt_f32_e64 s[2:3], s2, v15
	s_and_b64 s[2:3], s[2:3], s[24:25]
	s_andn2_b64 s[2:3], s[2:3], s[0:1]
	s_or_b64 s[2:3], s[2:3], vcc
	s_and_b64 vcc, exec, s[2:3]
	s_cbranch_vccnz .LBB0_541

; template <int MODE>
; DI void bias_init(f32x16& s0, f32x16& s1, const TP& tp, float fbm, int hi) {
; #pragma unroll
;     for (int r = 0; r < 16; ++r) {
;         const int kvc = 16 * (r >> 3) + (r & 7);
;         if (MODE == 0) { s0[r] = __builtin_fmaf(-L2E, tp.cs[kvc + 8 * hi], fbm); s1[r] = __builtin_fmaf(-L2E, tp.cs[kvc + 32 + 8 * hi], fbm); }
;         else { s0[r] = __builtin_fmaf(tp.sl, (float)kvc, fbm); s1[r] = __builtin_fmaf(tp.sl, (float)(kvc + 32), fbm); }
;     }
; }
; DI float max3_asm(float a, float b, float c) { float r; asm("v_max3_f32 %0, %1, %2, %3" : "=v"(r) : "v"(a), "v"(b), "v"(c)); return r; }
; template <bool MASK>
; DI float mask_rowmax(f32x16& s0, f32x16& s1, const TP& tp) {
;     if (MASK) {
; #pragma unroll
;         for (int r = 0; r < 16; ++r) {
;             const int kvc = 16 * (r >> 3) + (r & 7);
;             const bool v0 = tp.sel && (kvc <= tp.lim) && (kvc > tp.lim2), v1 = tp.sel && (kvc + 32 <= tp.lim) && (kvc + 32 > tp.lim2);
;             s0[r] = v0 ? s0[r] : -1e30f; s1[r] = v1 ? s1[r] : -1e30f;
;         }
;     }
;     const float seed = __builtin_fminf(s0[15], s1[15]);
;     float ma = seed, mb = seed;
; #pragma unroll
;     for (int r = 0; r < 16; r += 2) { ma = max3_asm(ma, s0[r], s1[r]); mb = max3_asm(mb, s0[r + 1], s1[r + 1]); }
;     const float mx = fmaxf(ma, mb);
;     return fmaxf(mx, __shfl_xor(mx, 32));
; }
; template <int MODE, bool MASK, bool WITH_O>
; DI void attn_tile_t(lptr Kt, lptr Vt, const bf16x8 (&qf)[4], f32x16& o0, f32x16& o1, RowState& rs, const TP& tp, int lane) {
;     const int hi = lane >> 5;
;     f32x16 s0, s1;
;     bias_init<MODE>(s0, s1, tp, tp.fb - rs.mref, hi);
;     qk_acc(Kt, qf, s0, s1, lane);
;     const float mx = mask_rowmax<MASK>(s0, s1, tp);
;     const bool was = rs.seen; rs.seen = was || (mx > -1e29f);
;     const bool trig = (mx > 8.f) || (!was && mx > -1e29f && mx < -8.f);
;     if (__builtin_expect(__any(trig), 0)) {
; DI void cmpwin_unit(const Params& P, lptr L, int u, int tid, int lane, int wid) {
;     ...
;             const int kv0 = (jw0 + jt) * 64;
;             TP tp; tp.cs = nullptr; tp.sl = sl; tp.fb = sl * (float)(kv0 + 8 * hi - t); tp.lim = t - kv0 - 8 * hi; tp.lim2 = tp.lim - 512; tp.sel = true;
;             const bool full = (kv0 + 63 <= tq0) && (tq0 + 31 - kv0 < 512);
;             attn_tile<1>(Kt, Vt, qf, o0, o1, rs, tp, !full, lane);
.LBB0_581:
	s_and_b32 s54, s53, 1
	s_mul_i32 s2, s54, 0x2400
	v_add_u32_e32 v34, s43, v161
	s_add_i32 s55, s2, 0
	s_add_i32 s2, s43, 63
	v_cvt_f32_i32_e32 v34, v34
	s_cmp_gt_u32 s2, s81
	s_cselect_b64 s[2:3], -1, 0
	s_cmp_lt_i32 s43, s23
	s_cselect_b64 s[28:29], -1, 0
	s_or_b64 s[2:3], s[2:3], s[28:29]
	v_mul_f32_e32 v216, v150, v34
	s_andn2_b64 vcc, exec, s[2:3]
	s_mov_b64 s[2:3], -1
	s_cbranch_vccz .LBB0_590
	s_mov_b32 s2, 2.0
	v_sub_f32_e32 v34, v216, v215
	s_mov_b32 s3, 0x40400000
	v_pk_fma_f32 v[84:85], v[166:167], s[2:3], v[34:35] op_sel_hi:[1,1,0]
	s_mov_b32 s2, 4.0
	s_mov_b32 s3, 0x40a00000
	v_pk_fma_f32 v[86:87], v[166:167], s[2:3], v[34:35] op_sel_hi:[1,1,0]
	s_mov_b32 s2, 0x40c00000
	s_mov_b32 s3, 0x40e00000
	v_pk_fma_f32 v[88:89], v[166:167], s[2:3], v[34:35] op_sel_hi:[1,1,0]
	s_mov_b32 s2, 0x41800000
	s_mov_b32 s3, 0x41880000
	v_pk_fma_f32 v[90:91], v[166:167], s[2:3], v[34:35] op_sel_hi:[1,1,0]
	s_mov_b32 s2, 0x41900000
	s_mov_b32 s3, 0x41980000
	v_pk_fma_f32 v[92:93], v[166:167], s[2:3], v[34:35] op_sel_hi:[1,1,0]
	s_mov_b32 s2, 0x41a00000
	s_mov_b32 s3, 0x41a80000
	v_mov_b32_e32 v151, v150
	v_add3_u32 v62, s55, v131, v133
	v_fma_f32 v82, 0, v150, v34
	v_add_f32_e32 v83, v150, v34
	v_pk_fma_f32 v[94:95], v[166:167], s[2:3], v[34:35] op_sel_hi:[1,1,0]
	v_pk_fma_f32 v[96:97], v[166:167], s[18:19], v[34:35] op_sel_hi:[1,1,0]
	v_pk_fma_f32 v[80:81], v[150:151], s[4:5], v[34:35] op_sel_hi:[1,1,0]
	v_pk_fma_f32 v[78:79], v[150:151], s[14:15], v[34:35] op_sel_hi:[1,1,0]
	v_pk_fma_f32 v[76:77], v[150:151], s[16:17], v[34:35] op_sel_hi:[1,1,0]
	v_pk_fma_f32 v[74:75], v[150:151], s[94:95], v[34:35] op_sel_hi:[1,1,0]
	v_pk_fma_f32 v[72:73], v[150:151], s[96:97], v[34:35] op_sel_hi:[1,1,0]
	v_pk_fma_f32 v[70:71], v[150:151], s[84:85], v[34:35] op_sel_hi:[1,1,0]
	v_pk_fma_f32 v[68:69], v[150:151], s[72:73], v[34:35] op_sel_hi:[1,1,0]
	v_pk_fma_f32 v[66:67], v[168:169], s[44:45], v[34:35] op_sel_hi:[1,1,0]
	ds_read_b128 v[34:37], v62 offset:4608
	ds_read_b128 v[38:41], v62
	ds_read_b128 v[42:45], v62 offset:32
	ds_read_b128 v[46:49], v62 offset:4640
	ds_read_b128 v[50:53], v62 offset:64
	ds_read_b128 v[54:57], v62 offset:4672
	ds_read_b128 v[58:61], v62 offset:96
	ds_read_b128 v[62:65], v62 offset:4704
	s_setprio 1
	s_waitcnt lgkmcnt(6)
	v_mfma_f32_32x32x16_bf16 v[82:97], v[38:41], v[98:101], v[82:97]
	v_mfma_f32_32x32x16_bf16 v[66:81], v[34:37], v[98:101], v[66:81]
	s_waitcnt lgkmcnt(5)
	v_mfma_f32_32x32x16_bf16 v[82:97], v[42:45], v[102:105], v[82:97]
	s_waitcnt lgkmcnt(4)
	v_mfma_f32_32x32x16_bf16 v[66:81], v[46:49], v[102:105], v[66:81]
	s_waitcnt lgkmcnt(3)
	v_mfma_f32_32x32x16_bf16 v[82:97], v[50:53], v[106:109], v[82:97]
	s_waitcnt lgkmcnt(2)
	v_mfma_f32_32x32x16_bf16 v[66:81], v[54:57], v[106:109], v[66:81]
	s_waitcnt lgkmcnt(1)
	v_mfma_f32_32x32x16_bf16 v[82:97], v[58:61], v[110:113], v[82:97]
	s_waitcnt lgkmcnt(0)
	v_mfma_f32_32x32x16_bf16 v[66:81], v[62:65], v[110:113], v[66:81]
	s_setprio 0
	s_nop 10
	v_max_f32_e32 v34, v81, v81
	v_max_f32_e32 v35, v97, v97
	v_min_f32_e32 v34, v35, v34
	v_max3_f32 v35, v34, v82, v66
	v_max3_f32 v34, v34, v83, v67
	s_mov_b32 s2, 0xefa18f08
	v_max3_f32 v35, v35, v84, v68
	v_max3_f32 v34, v34, v85, v69
	s_mov_b64 s[30:31], -1
	v_max3_f32 v35, v35, v86, v70
	v_max3_f32 v34, v34, v87, v71
	s_nop 0
	v_max3_f32 v35, v35, v88, v72
	v_max3_f32 v34, v34, v89, v73
	s_nop 0
	v_max3_f32 v35, v35, v90, v74
	v_max3_f32 v34, v34, v91, v75
	s_nop 0
	v_max3_f32 v35, v35, v92, v76
	v_max3_f32 v34, v34, v93, v77
	s_nop 0
	v_max3_f32 v35, v35, v94, v78
	v_max3_f32 v34, v34, v95, v79
	s_nop 0
	v_max3_f32 v35, v35, v96, v80
	v_max3_f32 v34, v34, v97, v81
	s_nop 0
	v_max_f32_e32 v34, v34, v34
	v_max_f32_e32 v35, v35, v35
	v_max_f32_e32 v34, v35, v34
	v_mov_b32_e32 v35, v34
	s_nop 1
	v_permlane32_swap_b32_e32 v35, v34
	s_waitcnt lgkmcnt(0)
	v_max_f32_e32 v218, v34, v35
	v_cmp_lt_f32_e64 s[28:29], s2, v218
	s_mov_b32 s2, 0x41000000
	v_cmp_lt_f32_e32 vcc, s2, v218
	s_mov_b32 s30, 0xc1000000
	v_cmp_gt_f32_e64 s[30:31], s30, v218
	s_and_b64 s[30:31], s[30:31], s[28:29]
	s_andn2_b64 s[30:31], s[30:31], s[24:25]
	s_or_b64 s[30:31], s[30:31], vcc
	s_and_b64 vcc, exec, s[30:31]
	v_mov_b32_e32 v217, v163
	v_mov_b32_e32 v151, v215
	s_cbranch_vccnz .LBB0_595

; #define LAS __attribute__((address_space(3)))
; #define MFMA32(a, b, c) __builtin_amdgcn_mfma_f32_32x32x16_bf16((a), (b), (c), 0, 0, 0)
; DI void qk_acc(lptr Kt, const bf16x8 (&qf)[4], f32x16& s0, f32x16& s1, int lane) {
;     const int i = lane & 31, hi = lane >> 5;
;     const int krow = (i & 19) | ((i & 4) << 1) | ((i & 8) >> 1);
;     lptr kp = Kt + krow * KPB + hi * 16;
;     bf16x8 a0[4], a1[4];
; #pragma unroll
;     for (int d0 = 0; d0 < 4; ++d0) { a0[d0] = *(LAS bf16x8*)(kp + d0 * 32); a1[d0] = *(LAS bf16x8*)(kp + 32 * KPB + d0 * 32); }
;     __builtin_amdgcn_s_setprio(1);
; #pragma unroll
;     for (int d0 = 0; d0 < 4; ++d0) { s0 = MFMA32(a0[d0], qf[d0], s0); s1 = MFMA32(a1[d0], qf[d0], s1); }
;     __builtin_amdgcn_s_setprio(0);
; }
; template <int MODE>
; DI void bias_init(f32x16& s0, f32x16& s1, const TP& tp, float fbm, int hi) {
; #pragma unroll
;     for (int r = 0; r < 16; ++r) {
;         const int kvc = 16 * (r >> 3) + (r & 7);
;         if (MODE == 0) { s0[r] = __builtin_fmaf(-L2E, tp.cs[kvc + 8 * hi], fbm); s1[r] = __builtin_fmaf(-L2E, tp.cs[kvc + 32 + 8 * hi], fbm); }
;         else { s0[r] = __builtin_fmaf(tp.sl, (float)kvc, fbm); s1[r] = __builtin_fmaf(tp.sl, (float)(kvc + 32), fbm); }
;     }
; }
.LBB0_590:
	s_and_b64 vcc, exec, s[2:3]
	s_cbranch_vccz .LBB0_586
	s_mov_b32 s2, 2.0
	v_sub_f32_e32 v50, v216, v215
	s_mov_b32 s3, 0x40400000
	v_add3_u32 v94, s55, v131, v133
	v_pk_fma_f32 v[36:37], v[166:167], s[2:3], v[50:51] op_sel_hi:[1,1,0]
	s_mov_b32 s2, 4.0
	ds_read_b128 v[66:69], v94 offset:4608
	ds_read_b128 v[70:73], v94
	ds_read_b128 v[74:77], v94 offset:32
	ds_read_b128 v[78:81], v94 offset:4640
	ds_read_b128 v[82:85], v94 offset:64
	ds_read_b128 v[86:89], v94 offset:4672
	ds_read_b128 v[90:93], v94 offset:96
	ds_read_b128 v[94:97], v94 offset:4704
	s_mov_b32 s3, 0x40a00000
	v_pk_fma_f32 v[38:39], v[166:167], s[2:3], v[50:51] op_sel_hi:[1,1,0]
	s_mov_b32 s2, 0x40c00000
	s_mov_b32 s3, 0x40e00000
	v_pk_fma_f32 v[40:41], v[166:167], s[2:3], v[50:51] op_sel_hi:[1,1,0]
	s_mov_b32 s2, 0x41800000
	s_mov_b32 s3, 0x41880000
	v_pk_fma_f32 v[42:43], v[166:167], s[2:3], v[50:51] op_sel_hi:[1,1,0]
	s_mov_b32 s2, 0x41900000
	s_mov_b32 s3, 0x41980000
	v_pk_fma_f32 v[44:45], v[166:167], s[2:3], v[50:51] op_sel_hi:[1,1,0]
	s_mov_b32 s2, 0x41a00000
	s_mov_b32 s3, 0x41a80000
	v_mov_b32_e32 v151, v150
	v_fma_f32 v34, 0, v150, v50
	v_add_f32_e32 v35, v150, v50
	v_pk_fma_f32 v[46:47], v[166:167], s[2:3], v[50:51] op_sel_hi:[1,1,0]
	v_pk_fma_f32 v[48:49], v[166:167], s[18:19], v[50:51] op_sel_hi:[1,1,0]
	v_pk_fma_f32 v[64:65], v[150:151], s[4:5], v[50:51] op_sel_hi:[1,1,0]
	v_pk_fma_f32 v[62:63], v[150:151], s[14:15], v[50:51] op_sel_hi:[1,1,0]
	v_pk_fma_f32 v[60:61], v[150:151], s[16:17], v[50:51] op_sel_hi:[1,1,0]
	v_pk_fma_f32 v[58:59], v[150:151], s[94:95], v[50:51] op_sel_hi:[1,1,0]
	v_pk_fma_f32 v[56:57], v[150:151], s[96:97], v[50:51] op_sel_hi:[1,1,0]
	v_pk_fma_f32 v[54:55], v[150:151], s[84:85], v[50:51] op_sel_hi:[1,1,0]
	v_pk_fma_f32 v[52:53], v[150:151], s[72:73], v[50:51] op_sel_hi:[1,1,0]
	v_pk_fma_f32 v[50:51], v[168:169], s[44:45], v[50:51] op_sel_hi:[1,1,0]
	s_setprio 1
	s_waitcnt lgkmcnt(6)
	v_mfma_f32_32x32x16_bf16 v[34:49], v[70:73], v[98:101], v[34:49]
	v_mfma_f32_32x32x16_bf16 v[50:65], v[66:69], v[98:101], v[50:65]
	s_waitcnt lgkmcnt(5)
	v_mfma_f32_32x32x16_bf16 v[34:49], v[74:77], v[102:105], v[34:49]
	s_waitcnt lgkmcnt(4)
	v_mfma_f32_32x32x16_bf16 v[50:65], v[78:81], v[102:105], v[50:65]
	s_waitcnt lgkmcnt(3)
	v_mfma_f32_32x32x16_bf16 v[34:49], v[82:85], v[106:109], v[34:49]
	s_waitcnt lgkmcnt(2)
	v_mfma_f32_32x32x16_bf16 v[50:65], v[86:89], v[106:109], v[50:65]
	s_waitcnt lgkmcnt(1)
	v_mfma_f32_32x32x16_bf16 v[34:49], v[90:93], v[110:113], v[34:49]
	s_waitcnt lgkmcnt(0)
; DI float max3_asm(float a, float b, float c) { float r; asm("v_max3_f32 %0, %1, %2, %3" : "=v"(r) : "v"(a), "v"(b), "v"(c)); return r; }
; template <bool MASK>
; DI float mask_rowmax(f32x16& s0, f32x16& s1, const TP& tp) {
;     if (MASK) {
; #pragma unroll
;         for (int r = 0; r < 16; ++r) {
;             const int kvc = 16 * (r >> 3) + (r & 7);
;             const bool v0 = tp.sel && (kvc <= tp.lim) && (kvc > tp.lim2), v1 = tp.sel && (kvc + 32 <= tp.lim) && (kvc + 32 > tp.lim2);
;             s0[r] = v0 ? s0[r] : -1e30f; s1[r] = v1 ? s1[r] : -1e30f;
;         }
;     }
;     const float seed = __builtin_fminf(s0[15], s1[15]);
;     float ma = seed, mb = seed;
; #pragma unroll
;     for (int r = 0; r < 16; r += 2) { ma = max3_asm(ma, s0[r], s1[r]); mb = max3_asm(mb, s0[r + 1], s1[r + 1]); }
;     const float mx = fmaxf(ma, mb);
;     return fmaxf(mx, __shfl_xor(mx, 32));
; }
; template <int MODE, bool MASK, bool WITH_O>
; DI void attn_tile_t(lptr Kt, lptr Vt, const bf16x8 (&qf)[4], f32x16& o0, f32x16& o1, RowState& rs, const TP& tp, int lane) {
;     const int hi = lane >> 5;
;     f32x16 s0, s1;
;     bias_init<MODE>(s0, s1, tp, tp.fb - rs.mref, hi);
;     qk_acc(Kt, qf, s0, s1, lane);
;     const float mx = mask_rowmax<MASK>(s0, s1, tp);
;     const bool was = rs.seen; rs.seen = was || (mx > -1e29f);
;     const bool trig = (mx > 8.f) || (!was && mx > -1e29f && mx < -8.f);
;     if (__builtin_expect(__any(trig), 0)) {
	v_mfma_f32_32x32x16_bf16 v[50:65], v[94:97], v[110:113], v[50:65]
	s_setprio 0
	v_add_u32_e32 v66, -1, v155
	v_cmp_gt_u32_e32 vcc, s10, v66
	s_mov_b32 s2, 0xefa18f08
	s_nop 5
	v_cndmask_b32_e32 v68, v210, v35, vcc
	v_cmp_gt_u32_e32 vcc, s10, v155
	v_subrev_u32_e32 v35, 32, v155
	s_nop 0
	v_cndmask_b32_e32 v75, v210, v34, vcc
	v_subrev_u32_e32 v34, 33, v155
	v_cmp_gt_u32_e32 vcc, s10, v34
	v_add_u32_e32 v34, -3, v155
	s_nop 0
	v_cndmask_b32_e32 v51, v210, v51, vcc
	v_cmp_gt_u32_e32 vcc, s10, v35
	v_add_u32_e32 v35, -2, v155
	s_nop 0
	v_cndmask_b32_e32 v67, v210, v50, vcc
	v_cmp_gt_u32_e32 vcc, s10, v34
	v_subrev_u32_e32 v34, 35, v155
	s_nop 0
	v_cndmask_b32_e32 v69, v210, v37, vcc
	v_cmp_gt_u32_e32 vcc, s10, v35
	v_subrev_u32_e32 v35, 34, v155
	v_subrev_u32_e32 v37, 20, v155
	v_cndmask_b32_e32 v72, v210, v36, vcc
	v_cmp_gt_u32_e32 vcc, s10, v34
	v_add_u32_e32 v34, -5, v155
	v_subrev_u32_e32 v36, 48, v155
	v_cndmask_b32_e32 v50, v210, v53, vcc
	v_cmp_gt_u32_e32 vcc, s10, v35
	v_add_u32_e32 v35, -4, v155
	s_nop 0
	v_cndmask_b32_e32 v66, v210, v52, vcc
	v_cmp_gt_u32_e32 vcc, s10, v34
	v_subrev_u32_e32 v34, 37, v155
	s_nop 0
	v_cndmask_b32_e32 v70, v210, v39, vcc
	v_cmp_gt_u32_e32 vcc, s10, v35
	v_subrev_u32_e32 v35, 36, v155
	s_nop 0
	v_cndmask_b32_e32 v73, v210, v38, vcc
	v_cmp_gt_u32_e32 vcc, s10, v34
	v_add_u32_e32 v34, -7, v155
	s_nop 0
	v_cndmask_b32_e32 v52, v210, v55, vcc
	v_cmp_gt_u32_e32 vcc, s10, v35
	v_add_u32_e32 v35, -6, v155
	s_nop 0
	v_cndmask_b32_e32 v54, v210, v54, vcc
	v_cmp_gt_u32_e32 vcc, s10, v34
	v_subrev_u32_e32 v34, 39, v155
	s_nop 0
	v_cndmask_b32_e32 v71, v210, v41, vcc
	v_cmp_gt_u32_e32 vcc, s10, v35
	v_subrev_u32_e32 v35, 38, v155
	s_nop 0
	v_cndmask_b32_e32 v74, v210, v40, vcc
	v_cmp_gt_u32_e32 vcc, s10, v34
	v_add_u32_e32 v34, -16, v155
	v_subrev_u32_e32 v40, 22, v155
	v_cndmask_b32_e32 v53, v210, v57, vcc
	v_cmp_gt_u32_e32 vcc, s10, v35
	v_subrev_u32_e32 v35, 17, v155
	s_nop 0
	v_cndmask_b32_e32 v55, v210, v56, vcc
	v_cmp_gt_u32_e32 vcc, s10, v35
	s_nop 1
	v_cndmask_b32_e32 v43, v210, v43, vcc
	v_cmp_gt_u32_e32 vcc, s10, v34
	v_subrev_u32_e32 v34, 49, v155
	s_nop 0
	v_cndmask_b32_e32 v57, v210, v42, vcc
	v_cmp_gt_u32_e32 vcc, s10, v34
	v_subrev_u32_e32 v34, 19, v155
	s_nop 0
	v_cndmask_b32_e32 v35, v210, v59, vcc
	v_cmp_gt_u32_e32 vcc, s10, v36
	v_subrev_u32_e32 v36, 18, v155
	s_nop 0
	v_cndmask_b32_e32 v41, v210, v58, vcc
	v_cmp_gt_u32_e32 vcc, s10, v34
	v_subrev_u32_e32 v34, 51, v155
	s_nop 0
	v_cndmask_b32_e32 v42, v210, v45, vcc
	v_cmp_gt_u32_e32 vcc, s10, v36
	v_subrev_u32_e32 v36, 50, v155
	s_nop 0
	v_cndmask_b32_e32 v56, v210, v44, vcc
	v_cmp_gt_u32_e32 vcc, s10, v34
	s_nop 1
	v_cndmask_b32_e32 v34, v210, v61, vcc
	v_cmp_gt_u32_e32 vcc, s10, v36
	v_subrev_u32_e32 v36, 21, v155
	s_nop 0
	v_cndmask_b32_e32 v38, v210, v60, vcc
	v_cmp_gt_u32_e32 vcc, s10, v36
	v_subrev_u32_e32 v36, 53, v155
	s_nop 0
	v_cndmask_b32_e32 v44, v210, v47, vcc
	v_cmp_gt_u32_e32 vcc, s10, v37
	v_subrev_u32_e32 v37, 52, v155
	s_nop 0
	v_cndmask_b32_e32 v46, v210, v46, vcc
	v_cmp_gt_u32_e32 vcc, s10, v36
	s_nop 1
	v_cndmask_b32_e32 v36, v210, v63, vcc
	v_cmp_gt_u32_e32 vcc, s10, v37
	v_subrev_u32_e32 v37, 23, v155
	s_nop 0
	v_cndmask_b32_e32 v39, v210, v62, vcc
	v_cmp_gt_u32_e32 vcc, s10, v37
	v_subrev_u32_e32 v37, 55, v155
	s_nop 0
	v_cndmask_b32_e32 v45, v210, v49, vcc
	v_cmp_gt_u32_e32 vcc, s10, v40
	v_max_f32_e32 v49, v45, v45
	v_subrev_u32_e32 v40, 54, v155
	v_cndmask_b32_e32 v47, v210, v48, vcc
	v_cmp_gt_u32_e32 vcc, s10, v37
	s_nop 1
	v_cndmask_b32_e32 v37, v210, v65, vcc
	v_max_f32_e32 v48, v37, v37
	v_min_f32_e32 v48, v49, v48
	v_max3_f32 v49, v48, v75, v67
	v_max3_f32 v48, v48, v68, v51
	v_cmp_gt_u32_e32 vcc, s10, v40
	v_max3_f32 v49, v49, v72, v66
	v_max3_f32 v48, v48, v69, v50
	s_nop 0
	v_max3_f32 v49, v49, v73, v54
	v_max3_f32 v48, v48, v70, v52
	s_nop 0
	v_cndmask_b32_e32 v40, v210, v64, vcc
	v_max3_f32 v49, v49, v74, v55
	v_max3_f32 v48, v48, v71, v53
	s_nop 0
	v_max3_f32 v49, v49, v57, v41
	v_max3_f32 v48, v48, v43, v35
	s_nop 0
	v_max3_f32 v49, v49, v56, v38
	v_max3_f32 v48, v48, v42, v34
	s_nop 0
	v_max3_f32 v49, v49, v46, v39
	v_max3_f32 v48, v48, v44, v36
	s_nop 0
	v_max3_f32 v49, v49, v47, v40
	v_max3_f32 v48, v48, v45, v37
	s_nop 0
	v_max_f32_e32 v48, v48, v48
	v_max_f32_e32 v49, v49, v49
	v_max_f32_e32 v48, v49, v48
	v_mov_b32_e32 v49, v48
	s_nop 1
	v_permlane32_swap_b32_e32 v49, v48
	s_waitcnt lgkmcnt(0)
	v_max_f32_e32 v48, v48, v49
	v_cmp_lt_f32_e64 s[28:29], s2, v48
	s_mov_b32 s2, 0x41000000
	v_cmp_lt_f32_e32 vcc, s2, v48
	s_mov_b32 s2, 0xc1000000
	v_cmp_gt_f32_e64 s[2:3], s2, v48
	s_and_b64 s[2:3], s[2:3], s[28:29]
	s_andn2_b64 s[2:3], s[2:3], s[24:25]
	s_or_b64 s[2:3], s[2:3], vcc
	s_and_b64 vcc, exec, s[2:3]
	s_cbranch_vccnz .LBB0_596

; template <int MODE>
; DI void bias_init(f32x16& s0, f32x16& s1, const TP& tp, float fbm, int hi) {
; #pragma unroll
;     for (int r = 0; r < 16; ++r) {
;         const int kvc = 16 * (r >> 3) + (r & 7);
;         if (MODE == 0) { s0[r] = __builtin_fmaf(-L2E, tp.cs[kvc + 8 * hi], fbm); s1[r] = __builtin_fmaf(-L2E, tp.cs[kvc + 32 + 8 * hi], fbm); }
;         else { s0[r] = __builtin_fmaf(tp.sl, (float)kvc, fbm); s1[r] = __builtin_fmaf(tp.sl, (float)(kvc + 32), fbm); }
;     }
; }
; DI float max3_asm(float a, float b, float c) { float r; asm("v_max3_f32 %0, %1, %2, %3" : "=v"(r) : "v"(a), "v"(b), "v"(c)); return r; }
; template <bool MASK>
; DI float mask_rowmax(f32x16& s0, f32x16& s1, const TP& tp) {
;     if (MASK) {
; #pragma unroll
;         for (int r = 0; r < 16; ++r) {
;             const int kvc = 16 * (r >> 3) + (r & 7);
;             const bool v0 = tp.sel && (kvc <= tp.lim) && (kvc > tp.lim2), v1 = tp.sel && (kvc + 32 <= tp.lim) && (kvc + 32 > tp.lim2);
;             s0[r] = v0 ? s0[r] : -1e30f; s1[r] = v1 ? s1[r] : -1e30f;
;         }
;     }
;     const float seed = __builtin_fminf(s0[15], s1[15]);
;     float ma = seed, mb = seed;
; #pragma unroll
;     for (int r = 0; r < 16; r += 2) { ma = max3_asm(ma, s0[r], s1[r]); mb = max3_asm(mb, s0[r + 1], s1[r + 1]); }
;     const float mx = fmaxf(ma, mb);
;     return fmaxf(mx, __shfl_xor(mx, 32));
; }
; template <int MODE, bool MASK, bool WITH_O>
; DI void attn_tile_t(lptr Kt, lptr Vt, const bf16x8 (&qf)[4], f32x16& o0, f32x16& o1, RowState& rs, const TP& tp, int lane) {
;     const int hi = lane >> 5;
;     f32x16 s0, s1;
;     bias_init<MODE>(s0, s1, tp, tp.fb - rs.mref, hi);
;     qk_acc(Kt, qf, s0, s1, lane);
;     const float mx = mask_rowmax<MASK>(s0, s1, tp);
;     const bool was = rs.seen; rs.seen = was || (mx > -1e29f);
;     const bool trig = (mx > 8.f) || (!was && mx > -1e29f && mx < -8.f);
;     if (__builtin_expect(__any(trig), 0)) {
; DI void slc_unit(const Params& P, lptr L, int u, int tid, int lane, int wid) {
;     ...
;         const int j = (int)list[jt], kv0 = j * 64;
;         const bool sel = (sm[ql * 8 + (j >> 5)] >> (j & 31)) & 1u;
;         if (__any(sel)) {
;             TP tp; tp.cs = nullptr; tp.sl = sl; tp.fb = sl * (float)(kv0 + 8 * hi - t); tp.lim = t - kv0 - 8 * hi; tp.lim2 = -(1 << 30); tp.sel = sel;
;             attn_tile<1>(Kt, Vt, qf, o0, o1, rs, tp, true, lane);
.LBB0_613:
	v_mov_b32_e32 v0, v253
	s_and_b32 s31, s0, 1
	v_and_b32_e32 v35, 31, v253
	s_waitcnt lgkmcnt(0)
	v_lshrrev_b32_e32 v36, v0, v255
	v_bfe_u32 v34, v255, v35, 1
	v_and_b32_e32 v35, 1, v36
	v_mov_b32_e32 v253, v254
	v_cmp_ne_u32_e32 vcc, 0, v34
	v_cmp_eq_u32_e64 s[28:29], 1, v35
	s_cbranch_vccz .LBB0_618
	v_lshl_or_b32 v0, v0, 6, v126
	v_sub_u32_e32 v34, v0, v91
	v_cvt_f32_i32_e32 v34, v34
	s_mov_b32 s0, 2.0
	v_sub_u32_e32 v152, v91, v0
	s_mov_b32 s1, 0x40400000
	v_cmp_lt_i32_e32 vcc, 54, v152
	v_fma_f32 v0, v150, v34, -v101
	s_cmp_eq_u64 vcc, exec
	s_cselect_b64 s[98:99], -1, 0
	s_orn2_b64 s[100:101], s[28:29], s[98:99]
	v_cndmask_b32_e64 v0, v210, v0, s[100:101]
	v_pk_fma_f32 v[36:37], v[94:95], s[0:1], v[0:1] op_sel_hi:[1,1,0]
	s_mov_b32 s0, 4.0
	s_mov_b32 s1, 0x40a00000
	v_pk_fma_f32 v[38:39], v[94:95], s[0:1], v[0:1] op_sel_hi:[1,1,0]
	s_mov_b32 s0, 0x40c00000
	s_mov_b32 s1, 0x40e00000
	v_pk_fma_f32 v[40:41], v[94:95], s[0:1], v[0:1] op_sel_hi:[1,1,0]
	s_mov_b32 s0, 0x41800000
	s_mov_b32 s1, 0x41880000
	v_pk_fma_f32 v[42:43], v[94:95], s[0:1], v[0:1] op_sel_hi:[1,1,0]
	s_mov_b32 s0, 0x41900000
	s_mov_b32 s1, 0x41980000
	v_pk_fma_f32 v[44:45], v[94:95], s[0:1], v[0:1] op_sel_hi:[1,1,0]
	s_mov_b32 s0, 0x41a00000
	s_mul_i32 s33, s31, 0x2400
	s_mov_b32 s1, 0x41a80000
	v_mov_b32_e32 v151, v150
	v_fma_f32 v34, 0, v150, v0
	v_add_f32_e32 v35, v150, v0
	v_pk_fma_f32 v[46:47], v[94:95], s[0:1], v[0:1] op_sel_hi:[1,1,0]
	v_pk_fma_f32 v[48:49], v[94:95], s[18:19], v[0:1] op_sel_hi:[1,1,0]
	v_pk_fma_f32 v[64:65], v[150:151], s[4:5], v[0:1] op_sel_hi:[1,1,0]
	v_pk_fma_f32 v[62:63], v[150:151], s[14:15], v[0:1] op_sel_hi:[1,1,0]
	v_pk_fma_f32 v[60:61], v[150:151], s[16:17], v[0:1] op_sel_hi:[1,1,0]
	v_pk_fma_f32 v[58:59], v[150:151], s[94:95], v[0:1] op_sel_hi:[1,1,0]
	v_pk_fma_f32 v[56:57], v[150:151], s[96:97], v[0:1] op_sel_hi:[1,1,0]
	v_pk_fma_f32 v[54:55], v[150:151], s[84:85], v[0:1] op_sel_hi:[1,1,0]
	v_pk_fma_f32 v[52:53], v[150:151], s[72:73], v[0:1] op_sel_hi:[1,1,0]
	v_pk_fma_f32 v[50:51], v[96:97], s[44:45], v[0:1] op_sel_hi:[1,1,0]
	v_add_u32_e32 v0, s33, v170
	ds_read_b128 v[102:105], v0 offset:4608
	ds_read_b128 v[106:109], v0
	ds_read_b128 v[110:113], v0 offset:32
	ds_read_b128 v[114:117], v0 offset:4640
	ds_read_b128 v[118:121], v0 offset:64
	ds_read_b128 v[158:161], v0 offset:4672
	ds_read_b128 v[162:165], v0 offset:96
	ds_read_b128 v[166:169], v0 offset:4704
	s_setprio 1
	s_waitcnt lgkmcnt(6)
	v_mfma_f32_32x32x16_bf16 v[34:49], v[106:109], v[66:69], v[34:49]
	v_mfma_f32_32x32x16_bf16 v[50:65], v[102:105], v[66:69], v[50:65]
	s_waitcnt lgkmcnt(5)
	v_mfma_f32_32x32x16_bf16 v[34:49], v[110:113], v[70:73], v[34:49]
	s_waitcnt lgkmcnt(4)
	v_mfma_f32_32x32x16_bf16 v[50:65], v[114:117], v[70:73], v[50:65]
	s_waitcnt lgkmcnt(3)
	v_mfma_f32_32x32x16_bf16 v[34:49], v[118:121], v[74:77], v[34:49]
	s_waitcnt lgkmcnt(2)
	v_mfma_f32_32x32x16_bf16 v[50:65], v[158:161], v[74:77], v[50:65]
	s_waitcnt lgkmcnt(1)
	v_mfma_f32_32x32x16_bf16 v[34:49], v[162:165], v[78:81], v[34:49]
	s_waitcnt lgkmcnt(0)
	v_mfma_f32_32x32x16_bf16 v[50:65], v[166:169], v[78:81], v[50:65]
	s_setprio 0
	s_and_b64 vcc, exec, s[98:99]
	s_cbranch_vccz .Lslc_masked
	s_nop 10
	v_max_f32_e32 v252, v65, v65
	v_max_f32_e32 v228, v49, v49
	v_min_f32_e32 v252, v228, v252
	v_max3_f32 v228, v252, v34, v50
	v_max3_f32 v252, v252, v35, v51
	s_mov_b32 s0, 0xefa18f08
	v_max3_f32 v228, v228, v36, v52
	v_max3_f32 v252, v252, v37, v53
	s_nop 0
	v_max3_f32 v228, v228, v38, v54
	v_max3_f32 v252, v252, v39, v55
	s_nop 0
	v_max3_f32 v228, v228, v40, v56
	v_max3_f32 v252, v252, v41, v57
	s_nop 0
	v_max3_f32 v228, v228, v42, v58
	v_max3_f32 v252, v252, v43, v59
	s_nop 0
	v_max3_f32 v228, v228, v44, v60
	v_max3_f32 v252, v252, v45, v61
	s_nop 0
	v_max3_f32 v228, v228, v46, v62
	v_max3_f32 v252, v252, v47, v63
	s_nop 0
	v_max3_f32 v228, v228, v48, v64
	v_max3_f32 v252, v252, v49, v65
	s_nop 0
	v_max_f32_e32 v252, v252, v252
	v_max_f32_e32 v228, v228, v228
	v_max_f32_e32 v252, v228, v252
	v_mov_b32_e32 v228, v252
	s_nop 1
	v_permlane32_swap_b32_e32 v228, v252
	s_waitcnt lgkmcnt(0)
	v_max_f32_e32 v252, v252, v228
	v_cmp_lt_f32_e64 s[28:29], s0, v252
	s_mov_b32 s0, 0x41000000
	v_cmp_lt_f32_e32 vcc, s0, v252
	s_mov_b32 s0, 0xc1000000
	v_cmp_gt_f32_e64 s[0:1], s0, v252
	s_and_b64 s[0:1], s[0:1], s[28:29]
	s_andn2_b64 s[0:1], s[0:1], s[22:23]
	s_or_b64 s[0:1], s[0:1], vcc
	s_and_b64 vcc, exec, s[0:1]
	s_cbranch_vccnz .Lsf_rare
; template <int MODE, bool MASK, bool WITH_O>
; DI void attn_tile_t(lptr Kt, lptr Vt, const bf16x8 (&qf)[4], f32x16& o0, f32x16& o1, RowState& rs, const TP& tp, int lane) {
;     ...
;     } else {
;         const int i = lane & 31;
;         lptr vp = Vt + i * KPB + hi * 16;
;         float sum = 0.f;
;     ...
;         PV_STEP(s0, 0, 0) PV_STEP(s0, 8, 32) PV_STEP(s1, 0, 64) PV_STEP(s1, 8, 96)
;     ...
;         rs.l += sum;
	v_exp_f32_e32 v252, v34
	v_exp_f32_e32 v103, v35
	v_exp_f32_e32 v111, v36
	v_exp_f32_e32 v105, v37
	v_add_f32_e32 v106, 0, v252
	v_add_f32_e32 v106, v103, v106
	v_add_f32_e32 v104, v111, v106
	v_exp_f32_e32 v106, v38
	v_exp_f32_e32 v107, v39
	v_add_u32_e32 v228, s33, v172
	v_exp_f32_e32 v108, v40
	ds_read_b128 v[236:239], v228 offset:18432
	ds_read_b128 v[240:243], v228 offset:23040
	v_add_f32_e32 v104, v105, v104
	v_exp_f32_e32 v109, v41
	v_add_f32_e32 v104, v106, v104
	v_add_f32_e32 v104, v107, v104
	v_add_f32_e32 v104, v108, v104
	v_add_f32_e32 v110, v109, v104
	v_cvt_pk_bf16_f32 v104, v252, v103
	v_cvt_pk_bf16_f32 v105, v111, v105
	v_cvt_pk_bf16_f32 v106, v106, v107
	v_cvt_pk_bf16_f32 v107, v108, v109
	s_or_b64 s[22:23], s[22:23], s[28:29]
	s_waitcnt lgkmcnt(1)
	v_mfma_f32_32x32x16_bf16 v[18:33], v[236:239], v[104:107], v[18:33]
	s_waitcnt lgkmcnt(0)
	v_mfma_f32_32x32x16_bf16 v[2:17], v[240:243], v[104:107], v[2:17]
	v_exp_f32_e32 v252, v42
	v_exp_f32_e32 v43, v43
	v_exp_f32_e32 v103, v44
	v_exp_f32_e32 v44, v45
	v_add_f32_e32 v229, v252, v110
	v_exp_f32_e32 v45, v46
	v_add_f32_e32 v229, v43, v229
	v_exp_f32_e32 v46, v47
	v_add_f32_e32 v42, v103, v229
	v_exp_f32_e32 v47, v48
	ds_read_b128 v[236:239], v228 offset:18464
	ds_read_b128 v[240:243], v228 offset:23072
	v_add_f32_e32 v42, v44, v42
	v_exp_f32_e32 v48, v49
	v_add_f32_e32 v42, v45, v42
	v_add_f32_e32 v42, v46, v42
	v_add_f32_e32 v42, v47, v42
	v_add_f32_e32 v229, v48, v42
	v_cvt_pk_bf16_f32 v42, v252, v43
	v_cvt_pk_bf16_f32 v43, v103, v44
	v_cvt_pk_bf16_f32 v44, v45, v46
	v_cvt_pk_bf16_f32 v45, v47, v48
	s_waitcnt lgkmcnt(1)
	s_nop 0
	v_mfma_f32_32x32x16_bf16 v[18:33], v[236:239], v[42:45], v[18:33]
	s_waitcnt lgkmcnt(0)
	v_mfma_f32_32x32x16_bf16 v[2:17], v[240:243], v[42:45], v[2:17]
	v_exp_f32_e32 v230, v50
	v_exp_f32_e32 v51, v51
	v_exp_f32_e32 v231, v52
	v_exp_f32_e32 v52, v53
	v_add_f32_e32 v229, v230, v229
	v_exp_f32_e32 v53, v54
	v_add_f32_e32 v229, v51, v229
	v_exp_f32_e32 v54, v55
	v_add_f32_e32 v50, v231, v229
	v_exp_f32_e32 v55, v56
	ds_read_b128 v[42:45], v228 offset:18496
	ds_read_b128 v[46:49], v228 offset:23104
	v_add_f32_e32 v50, v52, v50
	v_exp_f32_e32 v41, v57
	v_add_f32_e32 v50, v53, v50
	v_add_f32_e32 v50, v54, v50
	v_add_f32_e32 v50, v55, v50
	v_add_f32_e32 v56, v41, v50
	v_cvt_pk_bf16_f32 v50, v230, v51
	v_cvt_pk_bf16_f32 v51, v231, v52
	v_cvt_pk_bf16_f32 v52, v53, v54
	v_cvt_pk_bf16_f32 v53, v55, v41
	s_waitcnt lgkmcnt(1)
	s_nop 0
	v_mfma_f32_32x32x16_bf16 v[18:33], v[42:45], v[50:53], v[18:33]
	s_waitcnt lgkmcnt(0)
	v_mfma_f32_32x32x16_bf16 v[2:17], v[46:49], v[50:53], v[2:17]
	v_exp_f32_e32 v38, v58
	v_exp_f32_e32 v34, v59
	v_exp_f32_e32 v0, v60
	v_exp_f32_e32 v35, v61
	v_add_f32_e32 v41, v38, v56
	v_exp_f32_e32 v36, v62
	ds_read_b128 v[42:45], v228 offset:18528
	ds_read_b128 v[46:49], v228 offset:23136
	v_add_f32_e32 v41, v34, v41
	v_exp_f32_e32 v37, v63
	v_exp_f32_e32 v39, v64
	v_exp_f32_e32 v40, v65
	v_add_f32_e32 v41, v0, v41
	v_add_f32_e32 v41, v35, v41
	v_add_f32_e32 v41, v36, v41
	v_add_f32_e32 v41, v37, v41
	v_cvt_pk_bf16_f32 v34, v38, v34
	v_cvt_pk_bf16_f32 v35, v0, v35
	v_cvt_pk_bf16_f32 v36, v36, v37
	v_cvt_pk_bf16_f32 v37, v39, v40
	v_add_f32_e32 v41, v39, v41
	v_add_f32_e32 v41, v40, v41
	s_waitcnt lgkmcnt(1)
	v_mfma_f32_32x32x16_bf16 v[18:33], v[42:45], v[34:37], v[18:33]
	s_waitcnt lgkmcnt(0)
	v_mfma_f32_32x32x16_bf16 v[2:17], v[46:49], v[34:37], v[2:17]
	v_add_f32_e32 v100, v100, v41
	s_branch .LBB0_618

; DI float max3_asm(float a, float b, float c) { float r; asm("v_max3_f32 %0, %1, %2, %3" : "=v"(r) : "v"(a), "v"(b), "v"(c)); return r; }
; template <bool MASK>
; DI float mask_rowmax(f32x16& s0, f32x16& s1, const TP& tp) {
;     ...
;     const float seed = __builtin_fminf(s0[15], s1[15]);
;     float ma = seed, mb = seed;
; #pragma unroll
;     for (int r = 0; r < 16; r += 2) { ma = max3_asm(ma, s0[r], s1[r]); mb = max3_asm(mb, s0[r + 1], s1[r + 1]); }
;     const float mx = fmaxf(ma, mb);
;     return fmaxf(mx, __shfl_xor(mx, 32));
; }
; template <int MODE, bool MASK, bool WITH_O>
; DI void attn_tile_t(lptr Kt, lptr Vt, const bf16x8 (&qf)[4], f32x16& o0, f32x16& o1, RowState& rs, const TP& tp, int lane) {
;     const int hi = lane >> 5;
;     f32x16 s0, s1;
;     bias_init<MODE>(s0, s1, tp, tp.fb - rs.mref, hi);
;     qk_acc(Kt, qf, s0, s1, lane);
;     const float mx = mask_rowmax<MASK>(s0, s1, tp);
;     const bool was = rs.seen; rs.seen = was || (mx > -1e29f);
;     const bool trig = (mx > 8.f) || (!was && mx > -1e29f && mx < -8.f);
;     if (__builtin_expect(__any(trig), 0)) {
.Lslc_join:
	v_max_f32_e32 v49, v40, v40
	v_max_f32_e32 v57, v48, v48
	v_min_f32_e32 v49, v57, v49
	v_max3_f32 v57, v49, v106, v102
	v_max3_f32 v49, v49, v103, v51
	s_mov_b32 s0, 0xefa18f08
	v_max3_f32 v57, v57, v104, v50
	v_max3_f32 v49, v49, v105, v52
	s_nop 0
	v_max3_f32 v57, v57, v107, v53
	v_max3_f32 v49, v49, v108, v54
	s_nop 0
	v_max3_f32 v57, v57, v109, v55
	v_max3_f32 v49, v49, v110, v41
	s_nop 0
	v_max3_f32 v57, v57, v56, v38
	v_max3_f32 v49, v49, v43, v34
	s_nop 0
	v_max3_f32 v57, v57, v42, v0
	v_max3_f32 v49, v49, v44, v35
	s_nop 0
	v_max3_f32 v57, v57, v45, v36
	v_max3_f32 v49, v49, v46, v37
	s_nop 0
	v_max3_f32 v57, v57, v47, v39
	v_max3_f32 v49, v49, v48, v40
	s_nop 0
	v_max_f32_e32 v49, v49, v49
	v_max_f32_e32 v57, v57, v57
	v_max_f32_e32 v49, v57, v49
	v_mov_b32_e32 v57, v49
	s_nop 1
	v_permlane32_swap_b32_e32 v57, v49
	s_waitcnt lgkmcnt(0)
	v_max_f32_e32 v49, v49, v57
	v_cmp_lt_f32_e64 s[28:29], s0, v49
	s_mov_b32 s0, 0x41000000
	v_cmp_lt_f32_e32 vcc, s0, v49
	s_mov_b32 s0, 0xc1000000
	v_cmp_gt_f32_e64 s[0:1], s0, v49
	s_and_b64 s[0:1], s[0:1], s[28:29]
	s_andn2_b64 s[0:1], s[0:1], s[22:23]
	s_or_b64 s[0:1], s[0:1], vcc
	s_and_b64 vcc, exec, s[0:1]
	s_cbranch_vccnz .LBB0_622
